# scan: per-row v staged [row][step] and fetched eight steps at a time (two ds_read_b128 per 8 steps instead of a ds_read_b32 per step); all VALU->DPP dependences two instructions apart
# speedup vs baseline: 1.0016x; 1.0016x over previous
.LBB0_610:
	s_or_b64 exec, exec, s[0:1]
	s_waitcnt vmcnt(0) lgkmcnt(0)
	v_pk_mul_f32 v[8:9], v[42:43], v[34:35]
	v_pk_mul_f32 v[4:5], v[44:45], v[36:37]
	v_pk_mul_f32 v[10:11], v[8:9], v[8:9]
	v_pk_mul_f32 v[6:7], v[4:5], v[4:5]
	v_add_f32_e32 v3, v10, v11
	v_add_f32_e32 v3, v6, v3
	v_add_f32_e32 v3, v7, v3
	v_and_b32_e32 v13, 0xffff0000, v110
	v_lshlrev_b32_e32 v14, 16, v111
	v_add_f32_dpp v3, v3, v3 quad_perm:[1,0,3,2] row_mask:0xf bank_mask:0xf bound_ctrl:1
	v_and_b32_e32 v15, 0xffff0000, v111
	v_lshlrev_b32_e32 v18, 16, v113
	v_add_f32_dpp v3, v3, v3 quad_perm:[2,3,0,1] row_mask:0xf bank_mask:0xf bound_ctrl:1
	v_and_b32_e32 v19, 0xffff0000, v113
	s_nop 0
	v_add_f32_dpp v3, v3, v3 row_half_mirror row_mask:0xf bank_mask:0xf bound_ctrl:1
	s_nop 1
	v_add_f32_dpp v3, v3, v3 row_ror:8 row_mask:0xf bank_mask:0xf bound_ctrl:1
	v_mul_f32_e32 v6, 0x4f800000, v3
	v_cmp_gt_f32_e32 vcc, s74, v3
	s_nop 1
	v_cndmask_b32_e32 v3, v3, v6, vcc
	v_sqrt_f32_e32 v6, v3
	s_nop 0
	v_add_u32_e32 v7, -1, v6
	v_fma_f32 v10, -v7, v6, v3
	v_cmp_ge_f32_e64 s[14:15], 0, v10
	v_add_u32_e32 v10, 1, v6
	s_nop 0
	v_cndmask_b32_e64 v7, v6, v7, s[14:15]
	v_fma_f32 v6, -v10, v6, v3
	v_cmp_lt_f32_e64 s[14:15], 0, v6
	s_nop 1
	v_cndmask_b32_e64 v6, v7, v10, s[14:15]
	v_mul_f32_e32 v7, 0x37800000, v6
	v_cndmask_b32_e32 v6, v6, v7, vcc
	v_cmp_class_f32_e32 vcc, v3, v163
	s_nop 1
	v_cndmask_b32_e32 v3, v6, v3, vcc
	v_max_f32_e32 v3, 0x2b8cbccc, v3
	v_div_scale_f32 v6, s[0:1], v3, v3, 1.0
	v_rcp_f32_e32 v7, v6
	s_nop 0
	v_fma_f32 v10, -v6, v7, 1.0
	v_fmac_f32_e32 v7, v10, v7
	v_div_scale_f32 v10, vcc, 1.0, v3, 1.0
	v_mul_f32_e32 v11, v10, v7
	v_fma_f32 v12, -v6, v11, v10
	v_fmac_f32_e32 v11, v12, v7
	v_fma_f32 v6, -v6, v11, v10
	v_div_fmas_f32 v6, v6, v7, v11
	v_div_fixup_f32 v10, v6, v3, 1.0
	v_lshlrev_b32_e32 v12, 16, v110
	v_pk_mul_f32 v[6:7], v[4:5], v[10:11] op_sel_hi:[1,0]
	v_pk_mul_f32 v[4:5], v[8:9], v[10:11] op_sel_hi:[1,0]
	v_pk_add_f32 v[8:9], v[14:15], -1.0 op_sel_hi:[1,0]
	v_pk_add_f32 v[10:11], v[12:13], -1.0 op_sel_hi:[1,0]
	v_pk_fma_f32 v[8:9], v[48:49], v[8:9], 1.0 op_sel_hi:[1,1,0]
	v_pk_fma_f32 v[16:17], v[46:47], v[10:11], 1.0 op_sel_hi:[1,1,0]
	v_pk_mul_f32 v[10:11], v[36:37], v[8:9]
	v_pk_mul_f32 v[8:9], v[34:35], v[16:17]
	v_pk_mul_f32 v[14:15], v[6:7], v[14:15]
	v_pk_mul_f32 v[12:13], v[4:5], v[12:13]
	v_lshlrev_b32_e32 v16, 16, v112
	v_and_b32_e32 v17, 0xffff0000, v112
	ds_write_b128 v141, v[4:7]
	ds_write_b128 v141, v[38:41] offset:8192
	ds_write_b128 v141, v[12:15] offset:16384
	ds_write_b128 v141, v[8:11] offset:24576
	ds_write_b128 v141, v[16:19] offset:32768
	s_and_saveexec_b64 s[0:1], s[10:11]
	v_lshlrev_b32_e32 v4, 16, v106
	v_and_b32_e32 v5, 0xffff0000, v106
	v_lshlrev_b32_e32 v6, 16, v107
	v_and_b32_e32 v7, 0xffff0000, v107
	v_lshrrev_b32_e32 v184, 4, v142
	v_lshl_add_u32 v184, v98, 7, v184
	v_add_u32_e32 v184, 0xa000, v184
	ds_write2_b32 v184, v4, v5 offset1:32
	ds_write2_b32 v184, v6, v7 offset0:64 offset1:96
	s_or_b64 exec, exec, s[0:1]
	v_pk_mul_f32 v[8:9], v[42:43], v[50:51]
	v_pk_mul_f32 v[4:5], v[44:45], v[52:53]
	v_pk_mul_f32 v[10:11], v[8:9], v[8:9]
	v_pk_mul_f32 v[6:7], v[4:5], v[4:5]
	v_add_f32_e32 v3, v10, v11
	v_add_f32_e32 v3, v6, v3
	v_add_f32_e32 v3, v7, v3
	v_and_b32_e32 v13, 0xffff0000, v114
	v_lshlrev_b32_e32 v14, 16, v115
	v_add_f32_dpp v3, v3, v3 quad_perm:[1,0,3,2] row_mask:0xf bank_mask:0xf bound_ctrl:1
	v_and_b32_e32 v15, 0xffff0000, v115
	v_lshlrev_b32_e32 v18, 16, v117
	v_add_f32_dpp v3, v3, v3 quad_perm:[2,3,0,1] row_mask:0xf bank_mask:0xf bound_ctrl:1
	v_and_b32_e32 v19, 0xffff0000, v117
	s_nop 0
	v_add_f32_dpp v3, v3, v3 row_half_mirror row_mask:0xf bank_mask:0xf bound_ctrl:1
	s_nop 1
	v_add_f32_dpp v3, v3, v3 row_ror:8 row_mask:0xf bank_mask:0xf bound_ctrl:1
	v_mul_f32_e32 v6, 0x4f800000, v3
	v_cmp_gt_f32_e32 vcc, s74, v3
	s_nop 1
	v_cndmask_b32_e32 v3, v3, v6, vcc
	v_sqrt_f32_e32 v6, v3
	s_nop 0
	v_add_u32_e32 v7, -1, v6
	v_fma_f32 v10, -v7, v6, v3
	v_cmp_ge_f32_e64 s[14:15], 0, v10
	v_add_u32_e32 v10, 1, v6
	s_nop 0
	v_cndmask_b32_e64 v7, v6, v7, s[14:15]
	v_fma_f32 v6, -v10, v6, v3
	v_cmp_lt_f32_e64 s[14:15], 0, v6
	s_nop 1
	v_cndmask_b32_e64 v6, v7, v10, s[14:15]
	v_mul_f32_e32 v7, 0x37800000, v6
	v_cndmask_b32_e32 v6, v6, v7, vcc
	v_cmp_class_f32_e32 vcc, v3, v163
	s_nop 1
	v_cndmask_b32_e32 v3, v6, v3, vcc
	v_max_f32_e32 v3, 0x2b8cbccc, v3
	v_div_scale_f32 v6, s[0:1], v3, v3, 1.0
	v_rcp_f32_e32 v7, v6
	s_nop 0
	v_fma_f32 v10, -v6, v7, 1.0
	v_fmac_f32_e32 v7, v10, v7
	v_div_scale_f32 v10, vcc, 1.0, v3, 1.0
	v_mul_f32_e32 v11, v10, v7
	v_fma_f32 v12, -v6, v11, v10
	v_fmac_f32_e32 v11, v12, v7
	v_fma_f32 v6, -v6, v11, v10
	v_div_fmas_f32 v6, v6, v7, v11
	v_div_fixup_f32 v10, v6, v3, 1.0
	v_lshlrev_b32_e32 v12, 16, v114
	v_pk_mul_f32 v[6:7], v[4:5], v[10:11] op_sel_hi:[1,0]
	v_pk_mul_f32 v[4:5], v[8:9], v[10:11] op_sel_hi:[1,0]
	v_pk_add_f32 v[8:9], v[14:15], -1.0 op_sel_hi:[1,0]
	v_pk_add_f32 v[10:11], v[12:13], -1.0 op_sel_hi:[1,0]
	v_pk_fma_f32 v[8:9], v[48:49], v[8:9], 1.0 op_sel_hi:[1,1,0]
	v_pk_fma_f32 v[16:17], v[46:47], v[10:11], 1.0 op_sel_hi:[1,1,0]
	v_pk_mul_f32 v[10:11], v[52:53], v[8:9]
	v_pk_mul_f32 v[8:9], v[50:51], v[16:17]
	v_pk_mul_f32 v[14:15], v[6:7], v[14:15]
	v_pk_mul_f32 v[12:13], v[4:5], v[12:13]
	v_lshlrev_b32_e32 v16, 16, v116
	v_and_b32_e32 v17, 0xffff0000, v116
	ds_write_b128 v145, v[4:7]
	ds_write_b128 v145, v[54:57] offset:8192
	ds_write_b128 v145, v[12:15] offset:16384
	ds_write_b128 v145, v[8:11] offset:24576
	ds_write_b128 v145, v[16:19] offset:32768
	s_and_saveexec_b64 s[0:1], s[10:11]
	v_lshlrev_b32_e32 v4, 16, v108
	v_and_b32_e32 v5, 0xffff0000, v108
	v_lshlrev_b32_e32 v6, 16, v109
	v_and_b32_e32 v7, 0xffff0000, v109
	v_lshrrev_b32_e32 v184, 4, v144
	v_lshl_add_u32 v184, v98, 7, v184
	v_add_u32_e32 v184, 0xa000, v184
	ds_write2_b32 v184, v4, v5 offset1:32
	ds_write2_b32 v184, v6, v7 offset0:64 offset1:96
	s_or_b64 exec, exec, s[0:1]
	v_mov_b64_e32 v[4:5], s[18:19]

.LBB0_619:
	s_and_saveexec_b64 s[0:1], s[8:9]
	s_xor_b64 s[14:15], exec, s[0:1]
	s_cbranch_execz .LBB0_623
	v_and_b32_e32 v87, 1, v101
	v_mad_u32_u24 v0, v87, s75, 0
	v_lshl_add_u32 v84, v98, 2, v0
	v_lshl_add_u32 v85, v99, 7, v0
	v_lshl_add_u32 v86, v87, 14, v162
	ds_read_b128 v[176:179], v85 offset:40960
	ds_read_b128 v[180:183], v85 offset:40976
	ds_read_b128 v[2:5], v84 offset:0
	ds_read_b128 v[6:9], v84 offset:8192
	ds_read_b128 v[10:13], v84 offset:16384
	ds_read_b128 v[14:17], v84 offset:24576
	ds_read_b128 v[18:21], v84 offset:32768
	ds_read_b128 v[24:27], v84 offset:256
	ds_read_b128 v[28:31], v84 offset:8448
	ds_read_b128 v[32:35], v84 offset:16640
	ds_read_b128 v[36:39], v84 offset:24832
	ds_read_b128 v[40:43], v84 offset:33024
	v_add_u32_e32 v86, 0x15000, v86
	s_waitcnt lgkmcnt(5)
	v_pk_mul_f32 v[68:69], v[2:3], v[78:79]
	v_pk_mul_f32 v[70:71], v[176:177], v[14:15] op_sel_hi:[0,1]
	v_pk_mul_f32 v[72:73], v[176:177], v[16:17] op_sel_hi:[0,1]
	v_pk_fma_f32 v[68:69], v[4:5], v[80:81], v[68:69]
	v_pk_fma_f32 v[74:75], v[6:7], v[78:79], v[70:71]
	v_pk_fma_f32 v[76:77], v[8:9], v[80:81], v[72:73]
	v_add_f32_e32 v68, v68, v69
	ds_read_b128 v[46:49], v84 offset:512
	ds_read_b128 v[50:53], v84 offset:8704
	v_add_f32_dpp v68, v68, v68 quad_perm:[1,0,3,2] row_mask:0xf bank_mask:0xf bound_ctrl:1
	ds_read_b128 v[54:57], v84 offset:16896
	ds_read_b128 v[58:61], v84 offset:25088
	v_add_f32_dpp v68, v68, v68 quad_perm:[2,3,0,1] row_mask:0xf bank_mask:0xf bound_ctrl:1
	ds_read_b128 v[62:65], v84 offset:33280
	s_nop 0
	v_add_f32_dpp v68, v68, v68 row_half_mirror row_mask:0xf bank_mask:0xf bound_ctrl:1
	s_nop 1
	v_add_f32_dpp v68, v68, v68 row_ror:8 row_mask:0xf bank_mask:0xf bound_ctrl:1
	v_pk_fma_f32 v[78:79], v[10:11], v[68:69], v[74:75] op_sel_hi:[1,0,1] neg_lo:[0,1,0] neg_hi:[0,1,0]
	v_pk_fma_f32 v[80:81], v[12:13], v[68:69], v[76:77] op_sel_hi:[1,0,1] neg_lo:[0,1,0] neg_hi:[0,1,0]
	s_waitcnt lgkmcnt(5)
	v_pk_mul_f32 v[68:69], v[24:25], v[78:79]
	v_pk_mul_f32 v[82:83], v[18:19], v[78:79]
	v_pk_mul_f32 v[70:71], v[176:177], v[36:37] op_sel:[1,0]
	v_pk_fma_f32 v[68:69], v[26:27], v[80:81], v[68:69]
	v_pk_fma_f32 v[82:83], v[20:21], v[80:81], v[82:83]
	v_pk_mul_f32 v[72:73], v[176:177], v[38:39] op_sel:[1,0]
	v_add_f32_e32 v68, v68, v69
	v_add_f32_e32 v82, v82, v83
	v_pk_fma_f32 v[74:75], v[28:29], v[78:79], v[70:71]
	v_add_f32_dpp v68, v68, v68 quad_perm:[1,0,3,2] row_mask:0xf bank_mask:0xf bound_ctrl:1
	v_add_f32_dpp v82, v82, v82 row_ror:8 row_mask:0xf bank_mask:0xf bound_ctrl:1
	v_pk_fma_f32 v[76:77], v[30:31], v[80:81], v[72:73]
	v_add_f32_dpp v68, v68, v68 quad_perm:[2,3,0,1] row_mask:0xf bank_mask:0xf bound_ctrl:1
	ds_read_b128 v[106:109], v84 offset:768
	ds_read_b128 v[110:113], v84 offset:8960
	v_add_f32_dpp v68, v68, v68 row_half_mirror row_mask:0xf bank_mask:0xf bound_ctrl:1
	ds_read_b128 v[114:117], v84 offset:17152
	ds_read_b128 v[118:121], v84 offset:25344
	v_add_f32_dpp v68, v68, v68 row_ror:8 row_mask:0xf bank_mask:0xf bound_ctrl:1
	ds_read_b128 v[122:125], v84 offset:33536
	v_pk_fma_f32 v[78:79], v[32:33], v[68:69], v[74:75] op_sel_hi:[1,0,1] neg_lo:[0,1,0] neg_hi:[0,1,0]
	v_pk_fma_f32 v[80:81], v[34:35], v[68:69], v[76:77] op_sel_hi:[1,0,1] neg_lo:[0,1,0] neg_hi:[0,1,0]
	s_waitcnt lgkmcnt(5)
	v_pk_mul_f32 v[68:69], v[46:47], v[78:79]
	v_pk_mul_f32 v[88:89], v[40:41], v[78:79]
	v_pk_mul_f32 v[70:71], v[178:179], v[58:59] op_sel_hi:[0,1]
	v_pk_fma_f32 v[68:69], v[48:49], v[80:81], v[68:69]
	v_pk_fma_f32 v[88:89], v[42:43], v[80:81], v[88:89]
	v_pk_mul_f32 v[72:73], v[178:179], v[60:61] op_sel_hi:[0,1]
	v_add_f32_e32 v68, v68, v69
	v_add_f32_e32 v88, v88, v89
	v_pk_fma_f32 v[74:75], v[50:51], v[78:79], v[70:71]
	v_add_f32_dpp v68, v68, v68 quad_perm:[1,0,3,2] row_mask:0xf bank_mask:0xf bound_ctrl:1
	v_add_f32_dpp v88, v88, v88 row_ror:8 row_mask:0xf bank_mask:0xf bound_ctrl:1
	v_pk_fma_f32 v[76:77], v[52:53], v[80:81], v[72:73]
	v_add_f32_dpp v68, v68, v68 quad_perm:[2,3,0,1] row_mask:0xf bank_mask:0xf bound_ctrl:1
	ds_write2st64_b32 v86, v82, v88 offset0:0 offset1:2
	ds_read_b128 v[2:5], v84 offset:1024
	v_add_f32_dpp v68, v68, v68 row_half_mirror row_mask:0xf bank_mask:0xf bound_ctrl:1
	ds_read_b128 v[6:9], v84 offset:9216
	ds_read_b128 v[10:13], v84 offset:17408
	v_add_f32_dpp v68, v68, v68 row_ror:8 row_mask:0xf bank_mask:0xf bound_ctrl:1
	ds_read_b128 v[14:17], v84 offset:25600
	ds_read_b128 v[18:21], v84 offset:33792
	v_pk_fma_f32 v[78:79], v[54:55], v[68:69], v[74:75] op_sel_hi:[1,0,1] neg_lo:[0,1,0] neg_hi:[0,1,0]
	v_pk_fma_f32 v[80:81], v[56:57], v[68:69], v[76:77] op_sel_hi:[1,0,1] neg_lo:[0,1,0] neg_hi:[0,1,0]
	s_waitcnt lgkmcnt(6)
	v_pk_mul_f32 v[68:69], v[106:107], v[78:79]
	v_pk_mul_f32 v[82:83], v[62:63], v[78:79]
	v_pk_mul_f32 v[70:71], v[178:179], v[118:119] op_sel:[1,0]
	v_pk_fma_f32 v[68:69], v[108:109], v[80:81], v[68:69]
	v_pk_fma_f32 v[82:83], v[64:65], v[80:81], v[82:83]
	v_pk_mul_f32 v[72:73], v[178:179], v[120:121] op_sel:[1,0]
	v_add_f32_e32 v68, v68, v69
	v_add_f32_e32 v82, v82, v83
	v_pk_fma_f32 v[74:75], v[110:111], v[78:79], v[70:71]
	v_add_f32_dpp v68, v68, v68 quad_perm:[1,0,3,2] row_mask:0xf bank_mask:0xf bound_ctrl:1
	v_add_f32_dpp v82, v82, v82 row_ror:8 row_mask:0xf bank_mask:0xf bound_ctrl:1
	v_pk_fma_f32 v[76:77], v[112:113], v[80:81], v[72:73]
	v_add_f32_dpp v68, v68, v68 quad_perm:[2,3,0,1] row_mask:0xf bank_mask:0xf bound_ctrl:1
	ds_read_b128 v[24:27], v84 offset:1280
	ds_read_b128 v[28:31], v84 offset:9472
	v_add_f32_dpp v68, v68, v68 row_half_mirror row_mask:0xf bank_mask:0xf bound_ctrl:1
	ds_read_b128 v[32:35], v84 offset:17664
	ds_read_b128 v[36:39], v84 offset:25856
	v_add_f32_dpp v68, v68, v68 row_ror:8 row_mask:0xf bank_mask:0xf bound_ctrl:1
	ds_read_b128 v[40:43], v84 offset:34048
	v_pk_fma_f32 v[78:79], v[114:115], v[68:69], v[74:75] op_sel_hi:[1,0,1] neg_lo:[0,1,0] neg_hi:[0,1,0]
	v_pk_fma_f32 v[80:81], v[116:117], v[68:69], v[76:77] op_sel_hi:[1,0,1] neg_lo:[0,1,0] neg_hi:[0,1,0]
	s_waitcnt lgkmcnt(5)
	v_pk_mul_f32 v[68:69], v[2:3], v[78:79]
	v_pk_mul_f32 v[88:89], v[122:123], v[78:79]
	v_pk_mul_f32 v[70:71], v[180:181], v[14:15] op_sel_hi:[0,1]
	v_pk_fma_f32 v[68:69], v[4:5], v[80:81], v[68:69]
	v_pk_fma_f32 v[88:89], v[124:125], v[80:81], v[88:89]
	v_pk_mul_f32 v[72:73], v[180:181], v[16:17] op_sel_hi:[0,1]
	v_add_f32_e32 v68, v68, v69
	v_add_f32_e32 v88, v88, v89
	v_pk_fma_f32 v[74:75], v[6:7], v[78:79], v[70:71]
	v_add_f32_dpp v68, v68, v68 quad_perm:[1,0,3,2] row_mask:0xf bank_mask:0xf bound_ctrl:1
	v_add_f32_dpp v88, v88, v88 row_ror:8 row_mask:0xf bank_mask:0xf bound_ctrl:1
	v_pk_fma_f32 v[76:77], v[8:9], v[80:81], v[72:73]
	v_add_f32_dpp v68, v68, v68 quad_perm:[2,3,0,1] row_mask:0xf bank_mask:0xf bound_ctrl:1
	ds_write2st64_b32 v86, v82, v88 offset0:4 offset1:6
	ds_read_b128 v[46:49], v84 offset:1536
	v_add_f32_dpp v68, v68, v68 row_half_mirror row_mask:0xf bank_mask:0xf bound_ctrl:1
	ds_read_b128 v[50:53], v84 offset:9728
	ds_read_b128 v[54:57], v84 offset:17920
	v_add_f32_dpp v68, v68, v68 row_ror:8 row_mask:0xf bank_mask:0xf bound_ctrl:1
	ds_read_b128 v[58:61], v84 offset:26112
	ds_read_b128 v[62:65], v84 offset:34304
	v_pk_fma_f32 v[78:79], v[10:11], v[68:69], v[74:75] op_sel_hi:[1,0,1] neg_lo:[0,1,0] neg_hi:[0,1,0]
	v_pk_fma_f32 v[80:81], v[12:13], v[68:69], v[76:77] op_sel_hi:[1,0,1] neg_lo:[0,1,0] neg_hi:[0,1,0]
	s_waitcnt lgkmcnt(6)
	v_pk_mul_f32 v[68:69], v[24:25], v[78:79]
	v_pk_mul_f32 v[82:83], v[18:19], v[78:79]
	v_pk_mul_f32 v[70:71], v[180:181], v[36:37] op_sel:[1,0]
	v_pk_fma_f32 v[68:69], v[26:27], v[80:81], v[68:69]
	v_pk_fma_f32 v[82:83], v[20:21], v[80:81], v[82:83]
	v_pk_mul_f32 v[72:73], v[180:181], v[38:39] op_sel:[1,0]
	v_add_f32_e32 v68, v68, v69
	v_add_f32_e32 v82, v82, v83
	v_pk_fma_f32 v[74:75], v[28:29], v[78:79], v[70:71]
	v_add_f32_dpp v68, v68, v68 quad_perm:[1,0,3,2] row_mask:0xf bank_mask:0xf bound_ctrl:1
	v_add_f32_dpp v82, v82, v82 row_ror:8 row_mask:0xf bank_mask:0xf bound_ctrl:1
	v_pk_fma_f32 v[76:77], v[30:31], v[80:81], v[72:73]
	v_add_f32_dpp v68, v68, v68 quad_perm:[2,3,0,1] row_mask:0xf bank_mask:0xf bound_ctrl:1
	ds_read_b128 v[106:109], v84 offset:1792
	ds_read_b128 v[110:113], v84 offset:9984
	v_add_f32_dpp v68, v68, v68 row_half_mirror row_mask:0xf bank_mask:0xf bound_ctrl:1
	ds_read_b128 v[114:117], v84 offset:18176
	ds_read_b128 v[118:121], v84 offset:26368
	v_add_f32_dpp v68, v68, v68 row_ror:8 row_mask:0xf bank_mask:0xf bound_ctrl:1
	ds_read_b128 v[122:125], v84 offset:34560
	v_pk_fma_f32 v[78:79], v[32:33], v[68:69], v[74:75] op_sel_hi:[1,0,1] neg_lo:[0,1,0] neg_hi:[0,1,0]
	v_pk_fma_f32 v[80:81], v[34:35], v[68:69], v[76:77] op_sel_hi:[1,0,1] neg_lo:[0,1,0] neg_hi:[0,1,0]
	s_waitcnt lgkmcnt(5)
	v_pk_mul_f32 v[68:69], v[46:47], v[78:79]
	v_pk_mul_f32 v[88:89], v[40:41], v[78:79]
	v_pk_mul_f32 v[70:71], v[182:183], v[58:59] op_sel_hi:[0,1]
	v_pk_fma_f32 v[68:69], v[48:49], v[80:81], v[68:69]
	v_pk_fma_f32 v[88:89], v[42:43], v[80:81], v[88:89]
	v_pk_mul_f32 v[72:73], v[182:183], v[60:61] op_sel_hi:[0,1]
	v_add_f32_e32 v68, v68, v69
	v_add_f32_e32 v88, v88, v89
	v_pk_fma_f32 v[74:75], v[50:51], v[78:79], v[70:71]
	v_add_f32_dpp v68, v68, v68 quad_perm:[1,0,3,2] row_mask:0xf bank_mask:0xf bound_ctrl:1
	v_add_f32_dpp v88, v88, v88 row_ror:8 row_mask:0xf bank_mask:0xf bound_ctrl:1
	v_pk_fma_f32 v[76:77], v[52:53], v[80:81], v[72:73]
	v_add_f32_dpp v68, v68, v68 quad_perm:[2,3,0,1] row_mask:0xf bank_mask:0xf bound_ctrl:1
	ds_write2st64_b32 v86, v82, v88 offset0:8 offset1:10
	ds_read_b128 v[2:5], v84 offset:2048
	v_add_f32_dpp v68, v68, v68 row_half_mirror row_mask:0xf bank_mask:0xf bound_ctrl:1
	ds_read_b128 v[6:9], v84 offset:10240
	ds_read_b128 v[10:13], v84 offset:18432
	v_add_f32_dpp v68, v68, v68 row_ror:8 row_mask:0xf bank_mask:0xf bound_ctrl:1
	ds_read_b128 v[14:17], v84 offset:26624
	ds_read_b128 v[18:21], v84 offset:34816
	ds_read_b128 v[168:171], v85 offset:40992
	ds_read_b128 v[172:175], v85 offset:41008
	v_pk_fma_f32 v[78:79], v[54:55], v[68:69], v[74:75] op_sel_hi:[1,0,1] neg_lo:[0,1,0] neg_hi:[0,1,0]
	v_pk_fma_f32 v[80:81], v[56:57], v[68:69], v[76:77] op_sel_hi:[1,0,1] neg_lo:[0,1,0] neg_hi:[0,1,0]
	s_waitcnt lgkmcnt(8)
	v_pk_mul_f32 v[68:69], v[106:107], v[78:79]
	v_pk_mul_f32 v[82:83], v[62:63], v[78:79]
	v_pk_mul_f32 v[70:71], v[182:183], v[118:119] op_sel:[1,0]
	v_pk_fma_f32 v[68:69], v[108:109], v[80:81], v[68:69]
	v_pk_fma_f32 v[82:83], v[64:65], v[80:81], v[82:83]
	v_pk_mul_f32 v[72:73], v[182:183], v[120:121] op_sel:[1,0]
	v_add_f32_e32 v68, v68, v69
	v_add_f32_e32 v82, v82, v83
	v_pk_fma_f32 v[74:75], v[110:111], v[78:79], v[70:71]
	v_add_f32_dpp v68, v68, v68 quad_perm:[1,0,3,2] row_mask:0xf bank_mask:0xf bound_ctrl:1
	v_add_f32_dpp v82, v82, v82 row_ror:8 row_mask:0xf bank_mask:0xf bound_ctrl:1
	v_pk_fma_f32 v[76:77], v[112:113], v[80:81], v[72:73]
	v_add_f32_dpp v68, v68, v68 quad_perm:[2,3,0,1] row_mask:0xf bank_mask:0xf bound_ctrl:1
	ds_read_b128 v[24:27], v84 offset:2304
	ds_read_b128 v[28:31], v84 offset:10496
	v_add_f32_dpp v68, v68, v68 row_half_mirror row_mask:0xf bank_mask:0xf bound_ctrl:1
	ds_read_b128 v[32:35], v84 offset:18688
	ds_read_b128 v[36:39], v84 offset:26880
	v_add_f32_dpp v68, v68, v68 row_ror:8 row_mask:0xf bank_mask:0xf bound_ctrl:1
	ds_read_b128 v[40:43], v84 offset:35072
	v_pk_fma_f32 v[78:79], v[114:115], v[68:69], v[74:75] op_sel_hi:[1,0,1] neg_lo:[0,1,0] neg_hi:[0,1,0]
	v_pk_fma_f32 v[80:81], v[116:117], v[68:69], v[76:77] op_sel_hi:[1,0,1] neg_lo:[0,1,0] neg_hi:[0,1,0]
	s_waitcnt lgkmcnt(5)
	v_pk_mul_f32 v[68:69], v[2:3], v[78:79]
	v_pk_mul_f32 v[88:89], v[122:123], v[78:79]
	v_pk_mul_f32 v[70:71], v[168:169], v[14:15] op_sel_hi:[0,1]
	v_pk_fma_f32 v[68:69], v[4:5], v[80:81], v[68:69]
	v_pk_fma_f32 v[88:89], v[124:125], v[80:81], v[88:89]
	v_pk_mul_f32 v[72:73], v[168:169], v[16:17] op_sel_hi:[0,1]
	v_add_f32_e32 v68, v68, v69
	v_add_f32_e32 v88, v88, v89
	v_pk_fma_f32 v[74:75], v[6:7], v[78:79], v[70:71]
	v_add_f32_dpp v68, v68, v68 quad_perm:[1,0,3,2] row_mask:0xf bank_mask:0xf bound_ctrl:1
	v_add_f32_dpp v88, v88, v88 row_ror:8 row_mask:0xf bank_mask:0xf bound_ctrl:1
	v_pk_fma_f32 v[76:77], v[8:9], v[80:81], v[72:73]
	v_add_f32_dpp v68, v68, v68 quad_perm:[2,3,0,1] row_mask:0xf bank_mask:0xf bound_ctrl:1
	ds_write2st64_b32 v86, v82, v88 offset0:12 offset1:14
	ds_read_b128 v[46:49], v84 offset:2560
	v_add_f32_dpp v68, v68, v68 row_half_mirror row_mask:0xf bank_mask:0xf bound_ctrl:1
	ds_read_b128 v[50:53], v84 offset:10752
	ds_read_b128 v[54:57], v84 offset:18944
	v_add_f32_dpp v68, v68, v68 row_ror:8 row_mask:0xf bank_mask:0xf bound_ctrl:1
	ds_read_b128 v[58:61], v84 offset:27136
	ds_read_b128 v[62:65], v84 offset:35328
	v_pk_fma_f32 v[78:79], v[10:11], v[68:69], v[74:75] op_sel_hi:[1,0,1] neg_lo:[0,1,0] neg_hi:[0,1,0]
	v_pk_fma_f32 v[80:81], v[12:13], v[68:69], v[76:77] op_sel_hi:[1,0,1] neg_lo:[0,1,0] neg_hi:[0,1,0]
	s_waitcnt lgkmcnt(6)
	v_pk_mul_f32 v[68:69], v[24:25], v[78:79]
	v_pk_mul_f32 v[82:83], v[18:19], v[78:79]
	v_pk_mul_f32 v[70:71], v[168:169], v[36:37] op_sel:[1,0]
	v_pk_fma_f32 v[68:69], v[26:27], v[80:81], v[68:69]
	v_pk_fma_f32 v[82:83], v[20:21], v[80:81], v[82:83]
	v_pk_mul_f32 v[72:73], v[168:169], v[38:39] op_sel:[1,0]
	v_add_f32_e32 v68, v68, v69
	v_add_f32_e32 v82, v82, v83
	v_pk_fma_f32 v[74:75], v[28:29], v[78:79], v[70:71]
	v_add_f32_dpp v68, v68, v68 quad_perm:[1,0,3,2] row_mask:0xf bank_mask:0xf bound_ctrl:1
	v_add_f32_dpp v82, v82, v82 row_ror:8 row_mask:0xf bank_mask:0xf bound_ctrl:1
	v_pk_fma_f32 v[76:77], v[30:31], v[80:81], v[72:73]
	v_add_f32_dpp v68, v68, v68 quad_perm:[2,3,0,1] row_mask:0xf bank_mask:0xf bound_ctrl:1
	ds_read_b128 v[106:109], v84 offset:2816
	ds_read_b128 v[110:113], v84 offset:11008
	v_add_f32_dpp v68, v68, v68 row_half_mirror row_mask:0xf bank_mask:0xf bound_ctrl:1
	ds_read_b128 v[114:117], v84 offset:19200
	ds_read_b128 v[118:121], v84 offset:27392
	v_add_f32_dpp v68, v68, v68 row_ror:8 row_mask:0xf bank_mask:0xf bound_ctrl:1
	ds_read_b128 v[122:125], v84 offset:35584
	v_pk_fma_f32 v[78:79], v[32:33], v[68:69], v[74:75] op_sel_hi:[1,0,1] neg_lo:[0,1,0] neg_hi:[0,1,0]
	v_pk_fma_f32 v[80:81], v[34:35], v[68:69], v[76:77] op_sel_hi:[1,0,1] neg_lo:[0,1,0] neg_hi:[0,1,0]
	s_waitcnt lgkmcnt(5)
	v_pk_mul_f32 v[68:69], v[46:47], v[78:79]
	v_pk_mul_f32 v[88:89], v[40:41], v[78:79]
	v_pk_mul_f32 v[70:71], v[170:171], v[58:59] op_sel_hi:[0,1]
	v_pk_fma_f32 v[68:69], v[48:49], v[80:81], v[68:69]
	v_pk_fma_f32 v[88:89], v[42:43], v[80:81], v[88:89]
	v_pk_mul_f32 v[72:73], v[170:171], v[60:61] op_sel_hi:[0,1]
	v_add_f32_e32 v68, v68, v69
	v_add_f32_e32 v88, v88, v89
	v_pk_fma_f32 v[74:75], v[50:51], v[78:79], v[70:71]
	v_add_f32_dpp v68, v68, v68 quad_perm:[1,0,3,2] row_mask:0xf bank_mask:0xf bound_ctrl:1
	v_add_f32_dpp v88, v88, v88 row_ror:8 row_mask:0xf bank_mask:0xf bound_ctrl:1
	v_pk_fma_f32 v[76:77], v[52:53], v[80:81], v[72:73]
	v_add_f32_dpp v68, v68, v68 quad_perm:[2,3,0,1] row_mask:0xf bank_mask:0xf bound_ctrl:1
	ds_write2st64_b32 v86, v82, v88 offset0:16 offset1:18
	ds_read_b128 v[2:5], v84 offset:3072
	v_add_f32_dpp v68, v68, v68 row_half_mirror row_mask:0xf bank_mask:0xf bound_ctrl:1
	ds_read_b128 v[6:9], v84 offset:11264
	ds_read_b128 v[10:13], v84 offset:19456
	v_add_f32_dpp v68, v68, v68 row_ror:8 row_mask:0xf bank_mask:0xf bound_ctrl:1
	ds_read_b128 v[14:17], v84 offset:27648
	ds_read_b128 v[18:21], v84 offset:35840
	v_pk_fma_f32 v[78:79], v[54:55], v[68:69], v[74:75] op_sel_hi:[1,0,1] neg_lo:[0,1,0] neg_hi:[0,1,0]
	v_pk_fma_f32 v[80:81], v[56:57], v[68:69], v[76:77] op_sel_hi:[1,0,1] neg_lo:[0,1,0] neg_hi:[0,1,0]
	s_waitcnt lgkmcnt(6)
	v_pk_mul_f32 v[68:69], v[106:107], v[78:79]
	v_pk_mul_f32 v[82:83], v[62:63], v[78:79]
	v_pk_mul_f32 v[70:71], v[170:171], v[118:119] op_sel:[1,0]
	v_pk_fma_f32 v[68:69], v[108:109], v[80:81], v[68:69]
	v_pk_fma_f32 v[82:83], v[64:65], v[80:81], v[82:83]
	v_pk_mul_f32 v[72:73], v[170:171], v[120:121] op_sel:[1,0]
	v_add_f32_e32 v68, v68, v69
	v_add_f32_e32 v82, v82, v83
	v_pk_fma_f32 v[74:75], v[110:111], v[78:79], v[70:71]
	v_add_f32_dpp v68, v68, v68 quad_perm:[1,0,3,2] row_mask:0xf bank_mask:0xf bound_ctrl:1
	v_add_f32_dpp v82, v82, v82 row_ror:8 row_mask:0xf bank_mask:0xf bound_ctrl:1
	v_pk_fma_f32 v[76:77], v[112:113], v[80:81], v[72:73]
	v_add_f32_dpp v68, v68, v68 quad_perm:[2,3,0,1] row_mask:0xf bank_mask:0xf bound_ctrl:1
	ds_read_b128 v[24:27], v84 offset:3328
	ds_read_b128 v[28:31], v84 offset:11520
	v_add_f32_dpp v68, v68, v68 row_half_mirror row_mask:0xf bank_mask:0xf bound_ctrl:1
	ds_read_b128 v[32:35], v84 offset:19712
	ds_read_b128 v[36:39], v84 offset:27904
	v_add_f32_dpp v68, v68, v68 row_ror:8 row_mask:0xf bank_mask:0xf bound_ctrl:1
	ds_read_b128 v[40:43], v84 offset:36096
	v_pk_fma_f32 v[78:79], v[114:115], v[68:69], v[74:75] op_sel_hi:[1,0,1] neg_lo:[0,1,0] neg_hi:[0,1,0]
	v_pk_fma_f32 v[80:81], v[116:117], v[68:69], v[76:77] op_sel_hi:[1,0,1] neg_lo:[0,1,0] neg_hi:[0,1,0]
	s_waitcnt lgkmcnt(5)
	v_pk_mul_f32 v[68:69], v[2:3], v[78:79]
	v_pk_mul_f32 v[88:89], v[122:123], v[78:79]
	v_pk_mul_f32 v[70:71], v[172:173], v[14:15] op_sel_hi:[0,1]
	v_pk_fma_f32 v[68:69], v[4:5], v[80:81], v[68:69]
	v_pk_fma_f32 v[88:89], v[124:125], v[80:81], v[88:89]
	v_pk_mul_f32 v[72:73], v[172:173], v[16:17] op_sel_hi:[0,1]
	v_add_f32_e32 v68, v68, v69
	v_add_f32_e32 v88, v88, v89
	v_pk_fma_f32 v[74:75], v[6:7], v[78:79], v[70:71]
	v_add_f32_dpp v68, v68, v68 quad_perm:[1,0,3,2] row_mask:0xf bank_mask:0xf bound_ctrl:1
	v_add_f32_dpp v88, v88, v88 row_ror:8 row_mask:0xf bank_mask:0xf bound_ctrl:1
	v_pk_fma_f32 v[76:77], v[8:9], v[80:81], v[72:73]
	v_add_f32_dpp v68, v68, v68 quad_perm:[2,3,0,1] row_mask:0xf bank_mask:0xf bound_ctrl:1
	ds_write2st64_b32 v86, v82, v88 offset0:20 offset1:22
	ds_read_b128 v[46:49], v84 offset:3584
	v_add_f32_dpp v68, v68, v68 row_half_mirror row_mask:0xf bank_mask:0xf bound_ctrl:1
	ds_read_b128 v[50:53], v84 offset:11776
	ds_read_b128 v[54:57], v84 offset:19968
	v_add_f32_dpp v68, v68, v68 row_ror:8 row_mask:0xf bank_mask:0xf bound_ctrl:1
	ds_read_b128 v[58:61], v84 offset:28160
	ds_read_b128 v[62:65], v84 offset:36352
	v_pk_fma_f32 v[78:79], v[10:11], v[68:69], v[74:75] op_sel_hi:[1,0,1] neg_lo:[0,1,0] neg_hi:[0,1,0]
	v_pk_fma_f32 v[80:81], v[12:13], v[68:69], v[76:77] op_sel_hi:[1,0,1] neg_lo:[0,1,0] neg_hi:[0,1,0]
	s_waitcnt lgkmcnt(6)
	v_pk_mul_f32 v[68:69], v[24:25], v[78:79]
	v_pk_mul_f32 v[82:83], v[18:19], v[78:79]
	v_pk_mul_f32 v[70:71], v[172:173], v[36:37] op_sel:[1,0]
	v_pk_fma_f32 v[68:69], v[26:27], v[80:81], v[68:69]
	v_pk_fma_f32 v[82:83], v[20:21], v[80:81], v[82:83]
	v_pk_mul_f32 v[72:73], v[172:173], v[38:39] op_sel:[1,0]
	v_add_f32_e32 v68, v68, v69
	v_add_f32_e32 v82, v82, v83
	v_pk_fma_f32 v[74:75], v[28:29], v[78:79], v[70:71]
	v_add_f32_dpp v68, v68, v68 quad_perm:[1,0,3,2] row_mask:0xf bank_mask:0xf bound_ctrl:1
	v_add_f32_dpp v82, v82, v82 row_ror:8 row_mask:0xf bank_mask:0xf bound_ctrl:1
	v_pk_fma_f32 v[76:77], v[30:31], v[80:81], v[72:73]
	v_add_f32_dpp v68, v68, v68 quad_perm:[2,3,0,1] row_mask:0xf bank_mask:0xf bound_ctrl:1
	ds_read_b128 v[106:109], v84 offset:3840
	ds_read_b128 v[110:113], v84 offset:12032
	v_add_f32_dpp v68, v68, v68 row_half_mirror row_mask:0xf bank_mask:0xf bound_ctrl:1
	ds_read_b128 v[114:117], v84 offset:20224
	ds_read_b128 v[118:121], v84 offset:28416
	v_add_f32_dpp v68, v68, v68 row_ror:8 row_mask:0xf bank_mask:0xf bound_ctrl:1
	ds_read_b128 v[122:125], v84 offset:36608
	v_pk_fma_f32 v[78:79], v[32:33], v[68:69], v[74:75] op_sel_hi:[1,0,1] neg_lo:[0,1,0] neg_hi:[0,1,0]
	v_pk_fma_f32 v[80:81], v[34:35], v[68:69], v[76:77] op_sel_hi:[1,0,1] neg_lo:[0,1,0] neg_hi:[0,1,0]
	s_waitcnt lgkmcnt(5)
	v_pk_mul_f32 v[68:69], v[46:47], v[78:79]
	v_pk_mul_f32 v[88:89], v[40:41], v[78:79]
	v_pk_mul_f32 v[70:71], v[174:175], v[58:59] op_sel_hi:[0,1]
	v_pk_fma_f32 v[68:69], v[48:49], v[80:81], v[68:69]
	v_pk_fma_f32 v[88:89], v[42:43], v[80:81], v[88:89]
	v_pk_mul_f32 v[72:73], v[174:175], v[60:61] op_sel_hi:[0,1]
	v_add_f32_e32 v68, v68, v69
	v_add_f32_e32 v88, v88, v89
	v_pk_fma_f32 v[74:75], v[50:51], v[78:79], v[70:71]
	v_add_f32_dpp v68, v68, v68 quad_perm:[1,0,3,2] row_mask:0xf bank_mask:0xf bound_ctrl:1
	v_add_f32_dpp v88, v88, v88 row_ror:8 row_mask:0xf bank_mask:0xf bound_ctrl:1
	v_pk_fma_f32 v[76:77], v[52:53], v[80:81], v[72:73]
	v_add_f32_dpp v68, v68, v68 quad_perm:[2,3,0,1] row_mask:0xf bank_mask:0xf bound_ctrl:1
	ds_write2st64_b32 v86, v82, v88 offset0:24 offset1:26
	ds_read_b128 v[2:5], v84 offset:4096
	v_add_f32_dpp v68, v68, v68 row_half_mirror row_mask:0xf bank_mask:0xf bound_ctrl:1
	ds_read_b128 v[6:9], v84 offset:12288
	ds_read_b128 v[10:13], v84 offset:20480
	v_add_f32_dpp v68, v68, v68 row_ror:8 row_mask:0xf bank_mask:0xf bound_ctrl:1
	ds_read_b128 v[14:17], v84 offset:28672
	ds_read_b128 v[18:21], v84 offset:36864
	ds_read_b128 v[176:179], v85 offset:41024
	ds_read_b128 v[180:183], v85 offset:41040
	v_pk_fma_f32 v[78:79], v[54:55], v[68:69], v[74:75] op_sel_hi:[1,0,1] neg_lo:[0,1,0] neg_hi:[0,1,0]
	v_pk_fma_f32 v[80:81], v[56:57], v[68:69], v[76:77] op_sel_hi:[1,0,1] neg_lo:[0,1,0] neg_hi:[0,1,0]
	s_waitcnt lgkmcnt(8)
	v_pk_mul_f32 v[68:69], v[106:107], v[78:79]
	v_pk_mul_f32 v[82:83], v[62:63], v[78:79]
	v_pk_mul_f32 v[70:71], v[174:175], v[118:119] op_sel:[1,0]
	v_pk_fma_f32 v[68:69], v[108:109], v[80:81], v[68:69]
	v_pk_fma_f32 v[82:83], v[64:65], v[80:81], v[82:83]
	v_pk_mul_f32 v[72:73], v[174:175], v[120:121] op_sel:[1,0]
	v_add_f32_e32 v68, v68, v69
	v_add_f32_e32 v82, v82, v83
	v_pk_fma_f32 v[74:75], v[110:111], v[78:79], v[70:71]
	v_add_f32_dpp v68, v68, v68 quad_perm:[1,0,3,2] row_mask:0xf bank_mask:0xf bound_ctrl:1
	v_add_f32_dpp v82, v82, v82 row_ror:8 row_mask:0xf bank_mask:0xf bound_ctrl:1
	v_pk_fma_f32 v[76:77], v[112:113], v[80:81], v[72:73]
	v_add_f32_dpp v68, v68, v68 quad_perm:[2,3,0,1] row_mask:0xf bank_mask:0xf bound_ctrl:1
	ds_read_b128 v[24:27], v84 offset:4352
	ds_read_b128 v[28:31], v84 offset:12544
	v_add_f32_dpp v68, v68, v68 row_half_mirror row_mask:0xf bank_mask:0xf bound_ctrl:1
	ds_read_b128 v[32:35], v84 offset:20736
	ds_read_b128 v[36:39], v84 offset:28928
	v_add_f32_dpp v68, v68, v68 row_ror:8 row_mask:0xf bank_mask:0xf bound_ctrl:1
	ds_read_b128 v[40:43], v84 offset:37120
	v_pk_fma_f32 v[78:79], v[114:115], v[68:69], v[74:75] op_sel_hi:[1,0,1] neg_lo:[0,1,0] neg_hi:[0,1,0]
	v_pk_fma_f32 v[80:81], v[116:117], v[68:69], v[76:77] op_sel_hi:[1,0,1] neg_lo:[0,1,0] neg_hi:[0,1,0]
	s_waitcnt lgkmcnt(5)
	v_pk_mul_f32 v[68:69], v[2:3], v[78:79]
	v_pk_mul_f32 v[88:89], v[122:123], v[78:79]
	v_pk_mul_f32 v[70:71], v[176:177], v[14:15] op_sel_hi:[0,1]
	v_pk_fma_f32 v[68:69], v[4:5], v[80:81], v[68:69]
	v_pk_fma_f32 v[88:89], v[124:125], v[80:81], v[88:89]
	v_pk_mul_f32 v[72:73], v[176:177], v[16:17] op_sel_hi:[0,1]
	v_add_f32_e32 v68, v68, v69
	v_add_f32_e32 v88, v88, v89
	v_pk_fma_f32 v[74:75], v[6:7], v[78:79], v[70:71]
	v_add_f32_dpp v68, v68, v68 quad_perm:[1,0,3,2] row_mask:0xf bank_mask:0xf bound_ctrl:1
	v_add_f32_dpp v88, v88, v88 row_ror:8 row_mask:0xf bank_mask:0xf bound_ctrl:1
	v_pk_fma_f32 v[76:77], v[8:9], v[80:81], v[72:73]
	v_add_f32_dpp v68, v68, v68 quad_perm:[2,3,0,1] row_mask:0xf bank_mask:0xf bound_ctrl:1
	ds_write2st64_b32 v86, v82, v88 offset0:28 offset1:30
	ds_read_b128 v[46:49], v84 offset:4608
	v_add_f32_dpp v68, v68, v68 row_half_mirror row_mask:0xf bank_mask:0xf bound_ctrl:1
	ds_read_b128 v[50:53], v84 offset:12800
	ds_read_b128 v[54:57], v84 offset:20992
	v_add_f32_dpp v68, v68, v68 row_ror:8 row_mask:0xf bank_mask:0xf bound_ctrl:1
	ds_read_b128 v[58:61], v84 offset:29184
	ds_read_b128 v[62:65], v84 offset:37376
	v_pk_fma_f32 v[78:79], v[10:11], v[68:69], v[74:75] op_sel_hi:[1,0,1] neg_lo:[0,1,0] neg_hi:[0,1,0]
	v_pk_fma_f32 v[80:81], v[12:13], v[68:69], v[76:77] op_sel_hi:[1,0,1] neg_lo:[0,1,0] neg_hi:[0,1,0]
	s_waitcnt lgkmcnt(6)
	v_pk_mul_f32 v[68:69], v[24:25], v[78:79]
	v_pk_mul_f32 v[82:83], v[18:19], v[78:79]
	v_pk_mul_f32 v[70:71], v[176:177], v[36:37] op_sel:[1,0]
	v_pk_fma_f32 v[68:69], v[26:27], v[80:81], v[68:69]
	v_pk_fma_f32 v[82:83], v[20:21], v[80:81], v[82:83]
	v_pk_mul_f32 v[72:73], v[176:177], v[38:39] op_sel:[1,0]
	v_add_f32_e32 v68, v68, v69
	v_add_f32_e32 v82, v82, v83
	v_pk_fma_f32 v[74:75], v[28:29], v[78:79], v[70:71]
	v_add_f32_dpp v68, v68, v68 quad_perm:[1,0,3,2] row_mask:0xf bank_mask:0xf bound_ctrl:1
	v_add_f32_dpp v82, v82, v82 row_ror:8 row_mask:0xf bank_mask:0xf bound_ctrl:1
	v_pk_fma_f32 v[76:77], v[30:31], v[80:81], v[72:73]
	v_add_f32_dpp v68, v68, v68 quad_perm:[2,3,0,1] row_mask:0xf bank_mask:0xf bound_ctrl:1
	ds_read_b128 v[106:109], v84 offset:4864
	ds_read_b128 v[110:113], v84 offset:13056
	v_add_f32_dpp v68, v68, v68 row_half_mirror row_mask:0xf bank_mask:0xf bound_ctrl:1
	ds_read_b128 v[114:117], v84 offset:21248
	ds_read_b128 v[118:121], v84 offset:29440
	v_add_f32_dpp v68, v68, v68 row_ror:8 row_mask:0xf bank_mask:0xf bound_ctrl:1
	ds_read_b128 v[122:125], v84 offset:37632
	v_pk_fma_f32 v[78:79], v[32:33], v[68:69], v[74:75] op_sel_hi:[1,0,1] neg_lo:[0,1,0] neg_hi:[0,1,0]
	v_pk_fma_f32 v[80:81], v[34:35], v[68:69], v[76:77] op_sel_hi:[1,0,1] neg_lo:[0,1,0] neg_hi:[0,1,0]
	s_waitcnt lgkmcnt(5)
	v_pk_mul_f32 v[68:69], v[46:47], v[78:79]
	v_pk_mul_f32 v[88:89], v[40:41], v[78:79]
	v_pk_mul_f32 v[70:71], v[178:179], v[58:59] op_sel_hi:[0,1]
	v_pk_fma_f32 v[68:69], v[48:49], v[80:81], v[68:69]
	v_pk_fma_f32 v[88:89], v[42:43], v[80:81], v[88:89]
	v_pk_mul_f32 v[72:73], v[178:179], v[60:61] op_sel_hi:[0,1]
	v_add_f32_e32 v68, v68, v69
	v_add_f32_e32 v88, v88, v89
	v_pk_fma_f32 v[74:75], v[50:51], v[78:79], v[70:71]
	v_add_f32_dpp v68, v68, v68 quad_perm:[1,0,3,2] row_mask:0xf bank_mask:0xf bound_ctrl:1
	v_add_f32_dpp v88, v88, v88 row_ror:8 row_mask:0xf bank_mask:0xf bound_ctrl:1
	v_pk_fma_f32 v[76:77], v[52:53], v[80:81], v[72:73]
	v_add_f32_dpp v68, v68, v68 quad_perm:[2,3,0,1] row_mask:0xf bank_mask:0xf bound_ctrl:1
	ds_write2st64_b32 v86, v82, v88 offset0:32 offset1:34
	ds_read_b128 v[2:5], v84 offset:5120
	v_add_f32_dpp v68, v68, v68 row_half_mirror row_mask:0xf bank_mask:0xf bound_ctrl:1
	ds_read_b128 v[6:9], v84 offset:13312
	ds_read_b128 v[10:13], v84 offset:21504
	v_add_f32_dpp v68, v68, v68 row_ror:8 row_mask:0xf bank_mask:0xf bound_ctrl:1
	ds_read_b128 v[14:17], v84 offset:29696
	ds_read_b128 v[18:21], v84 offset:37888
	v_pk_fma_f32 v[78:79], v[54:55], v[68:69], v[74:75] op_sel_hi:[1,0,1] neg_lo:[0,1,0] neg_hi:[0,1,0]
	v_pk_fma_f32 v[80:81], v[56:57], v[68:69], v[76:77] op_sel_hi:[1,0,1] neg_lo:[0,1,0] neg_hi:[0,1,0]
	s_waitcnt lgkmcnt(6)
	v_pk_mul_f32 v[68:69], v[106:107], v[78:79]
	v_pk_mul_f32 v[82:83], v[62:63], v[78:79]
	v_pk_mul_f32 v[70:71], v[178:179], v[118:119] op_sel:[1,0]
	v_pk_fma_f32 v[68:69], v[108:109], v[80:81], v[68:69]
	v_pk_fma_f32 v[82:83], v[64:65], v[80:81], v[82:83]
	v_pk_mul_f32 v[72:73], v[178:179], v[120:121] op_sel:[1,0]
	v_add_f32_e32 v68, v68, v69
	v_add_f32_e32 v82, v82, v83
	v_pk_fma_f32 v[74:75], v[110:111], v[78:79], v[70:71]
	v_add_f32_dpp v68, v68, v68 quad_perm:[1,0,3,2] row_mask:0xf bank_mask:0xf bound_ctrl:1
	v_add_f32_dpp v82, v82, v82 row_ror:8 row_mask:0xf bank_mask:0xf bound_ctrl:1
	v_pk_fma_f32 v[76:77], v[112:113], v[80:81], v[72:73]
	v_add_f32_dpp v68, v68, v68 quad_perm:[2,3,0,1] row_mask:0xf bank_mask:0xf bound_ctrl:1
	ds_read_b128 v[24:27], v84 offset:5376
	ds_read_b128 v[28:31], v84 offset:13568
	v_add_f32_dpp v68, v68, v68 row_half_mirror row_mask:0xf bank_mask:0xf bound_ctrl:1
	ds_read_b128 v[32:35], v84 offset:21760
	ds_read_b128 v[36:39], v84 offset:29952
	v_add_f32_dpp v68, v68, v68 row_ror:8 row_mask:0xf bank_mask:0xf bound_ctrl:1
	ds_read_b128 v[40:43], v84 offset:38144
	v_pk_fma_f32 v[78:79], v[114:115], v[68:69], v[74:75] op_sel_hi:[1,0,1] neg_lo:[0,1,0] neg_hi:[0,1,0]
	v_pk_fma_f32 v[80:81], v[116:117], v[68:69], v[76:77] op_sel_hi:[1,0,1] neg_lo:[0,1,0] neg_hi:[0,1,0]
	s_waitcnt lgkmcnt(5)
	v_pk_mul_f32 v[68:69], v[2:3], v[78:79]
	v_pk_mul_f32 v[88:89], v[122:123], v[78:79]
	v_pk_mul_f32 v[70:71], v[180:181], v[14:15] op_sel_hi:[0,1]
	v_pk_fma_f32 v[68:69], v[4:5], v[80:81], v[68:69]
	v_pk_fma_f32 v[88:89], v[124:125], v[80:81], v[88:89]
	v_pk_mul_f32 v[72:73], v[180:181], v[16:17] op_sel_hi:[0,1]
	v_add_f32_e32 v68, v68, v69
	v_add_f32_e32 v88, v88, v89
	v_pk_fma_f32 v[74:75], v[6:7], v[78:79], v[70:71]
	v_add_f32_dpp v68, v68, v68 quad_perm:[1,0,3,2] row_mask:0xf bank_mask:0xf bound_ctrl:1
	v_add_f32_dpp v88, v88, v88 row_ror:8 row_mask:0xf bank_mask:0xf bound_ctrl:1
	v_pk_fma_f32 v[76:77], v[8:9], v[80:81], v[72:73]
	v_add_f32_dpp v68, v68, v68 quad_perm:[2,3,0,1] row_mask:0xf bank_mask:0xf bound_ctrl:1
	ds_write2st64_b32 v86, v82, v88 offset0:36 offset1:38
	ds_read_b128 v[46:49], v84 offset:5632
	v_add_f32_dpp v68, v68, v68 row_half_mirror row_mask:0xf bank_mask:0xf bound_ctrl:1
	ds_read_b128 v[50:53], v84 offset:13824
	ds_read_b128 v[54:57], v84 offset:22016
	v_add_f32_dpp v68, v68, v68 row_ror:8 row_mask:0xf bank_mask:0xf bound_ctrl:1
	ds_read_b128 v[58:61], v84 offset:30208
	ds_read_b128 v[62:65], v84 offset:38400
	v_pk_fma_f32 v[78:79], v[10:11], v[68:69], v[74:75] op_sel_hi:[1,0,1] neg_lo:[0,1,0] neg_hi:[0,1,0]
	v_pk_fma_f32 v[80:81], v[12:13], v[68:69], v[76:77] op_sel_hi:[1,0,1] neg_lo:[0,1,0] neg_hi:[0,1,0]
	s_waitcnt lgkmcnt(6)
	v_pk_mul_f32 v[68:69], v[24:25], v[78:79]
	v_pk_mul_f32 v[82:83], v[18:19], v[78:79]
	v_pk_mul_f32 v[70:71], v[180:181], v[36:37] op_sel:[1,0]
	v_pk_fma_f32 v[68:69], v[26:27], v[80:81], v[68:69]
	v_pk_fma_f32 v[82:83], v[20:21], v[80:81], v[82:83]
	v_pk_mul_f32 v[72:73], v[180:181], v[38:39] op_sel:[1,0]
	v_add_f32_e32 v68, v68, v69
	v_add_f32_e32 v82, v82, v83
	v_pk_fma_f32 v[74:75], v[28:29], v[78:79], v[70:71]
	v_add_f32_dpp v68, v68, v68 quad_perm:[1,0,3,2] row_mask:0xf bank_mask:0xf bound_ctrl:1
	v_add_f32_dpp v82, v82, v82 row_ror:8 row_mask:0xf bank_mask:0xf bound_ctrl:1
	v_pk_fma_f32 v[76:77], v[30:31], v[80:81], v[72:73]
	v_add_f32_dpp v68, v68, v68 quad_perm:[2,3,0,1] row_mask:0xf bank_mask:0xf bound_ctrl:1
	ds_read_b128 v[106:109], v84 offset:5888
	ds_read_b128 v[110:113], v84 offset:14080
	v_add_f32_dpp v68, v68, v68 row_half_mirror row_mask:0xf bank_mask:0xf bound_ctrl:1
	ds_read_b128 v[114:117], v84 offset:22272
	ds_read_b128 v[118:121], v84 offset:30464
	v_add_f32_dpp v68, v68, v68 row_ror:8 row_mask:0xf bank_mask:0xf bound_ctrl:1
	ds_read_b128 v[122:125], v84 offset:38656
	v_pk_fma_f32 v[78:79], v[32:33], v[68:69], v[74:75] op_sel_hi:[1,0,1] neg_lo:[0,1,0] neg_hi:[0,1,0]
	v_pk_fma_f32 v[80:81], v[34:35], v[68:69], v[76:77] op_sel_hi:[1,0,1] neg_lo:[0,1,0] neg_hi:[0,1,0]
	s_waitcnt lgkmcnt(5)
	v_pk_mul_f32 v[68:69], v[46:47], v[78:79]
	v_pk_mul_f32 v[88:89], v[40:41], v[78:79]
	v_pk_mul_f32 v[70:71], v[182:183], v[58:59] op_sel_hi:[0,1]
	v_pk_fma_f32 v[68:69], v[48:49], v[80:81], v[68:69]
	v_pk_fma_f32 v[88:89], v[42:43], v[80:81], v[88:89]
	v_pk_mul_f32 v[72:73], v[182:183], v[60:61] op_sel_hi:[0,1]
	v_add_f32_e32 v68, v68, v69
	v_add_f32_e32 v88, v88, v89
	v_pk_fma_f32 v[74:75], v[50:51], v[78:79], v[70:71]
	v_add_f32_dpp v68, v68, v68 quad_perm:[1,0,3,2] row_mask:0xf bank_mask:0xf bound_ctrl:1
	v_add_f32_dpp v88, v88, v88 row_ror:8 row_mask:0xf bank_mask:0xf bound_ctrl:1
	v_pk_fma_f32 v[76:77], v[52:53], v[80:81], v[72:73]
	v_add_f32_dpp v68, v68, v68 quad_perm:[2,3,0,1] row_mask:0xf bank_mask:0xf bound_ctrl:1
	ds_write2st64_b32 v86, v82, v88 offset0:40 offset1:42
	ds_read_b128 v[2:5], v84 offset:6144
	v_add_f32_dpp v68, v68, v68 row_half_mirror row_mask:0xf bank_mask:0xf bound_ctrl:1
	ds_read_b128 v[6:9], v84 offset:14336
	ds_read_b128 v[10:13], v84 offset:22528
	v_add_f32_dpp v68, v68, v68 row_ror:8 row_mask:0xf bank_mask:0xf bound_ctrl:1
	ds_read_b128 v[14:17], v84 offset:30720
	ds_read_b128 v[18:21], v84 offset:38912
	ds_read_b128 v[168:171], v85 offset:41056
	ds_read_b128 v[172:175], v85 offset:41072
	v_pk_fma_f32 v[78:79], v[54:55], v[68:69], v[74:75] op_sel_hi:[1,0,1] neg_lo:[0,1,0] neg_hi:[0,1,0]
	v_pk_fma_f32 v[80:81], v[56:57], v[68:69], v[76:77] op_sel_hi:[1,0,1] neg_lo:[0,1,0] neg_hi:[0,1,0]
	s_waitcnt lgkmcnt(8)
	v_pk_mul_f32 v[68:69], v[106:107], v[78:79]
	v_pk_mul_f32 v[82:83], v[62:63], v[78:79]
	v_pk_mul_f32 v[70:71], v[182:183], v[118:119] op_sel:[1,0]
	v_pk_fma_f32 v[68:69], v[108:109], v[80:81], v[68:69]
	v_pk_fma_f32 v[82:83], v[64:65], v[80:81], v[82:83]
	v_pk_mul_f32 v[72:73], v[182:183], v[120:121] op_sel:[1,0]
	v_add_f32_e32 v68, v68, v69
	v_add_f32_e32 v82, v82, v83
	v_pk_fma_f32 v[74:75], v[110:111], v[78:79], v[70:71]
	v_add_f32_dpp v68, v68, v68 quad_perm:[1,0,3,2] row_mask:0xf bank_mask:0xf bound_ctrl:1
	v_add_f32_dpp v82, v82, v82 row_ror:8 row_mask:0xf bank_mask:0xf bound_ctrl:1
	v_pk_fma_f32 v[76:77], v[112:113], v[80:81], v[72:73]
	v_add_f32_dpp v68, v68, v68 quad_perm:[2,3,0,1] row_mask:0xf bank_mask:0xf bound_ctrl:1
	ds_read_b128 v[24:27], v84 offset:6400
	ds_read_b128 v[28:31], v84 offset:14592
	v_add_f32_dpp v68, v68, v68 row_half_mirror row_mask:0xf bank_mask:0xf bound_ctrl:1
	ds_read_b128 v[32:35], v84 offset:22784
	ds_read_b128 v[36:39], v84 offset:30976
	v_add_f32_dpp v68, v68, v68 row_ror:8 row_mask:0xf bank_mask:0xf bound_ctrl:1
	ds_read_b128 v[40:43], v84 offset:39168
	v_pk_fma_f32 v[78:79], v[114:115], v[68:69], v[74:75] op_sel_hi:[1,0,1] neg_lo:[0,1,0] neg_hi:[0,1,0]
	v_pk_fma_f32 v[80:81], v[116:117], v[68:69], v[76:77] op_sel_hi:[1,0,1] neg_lo:[0,1,0] neg_hi:[0,1,0]
	s_waitcnt lgkmcnt(5)
	v_pk_mul_f32 v[68:69], v[2:3], v[78:79]
	v_pk_mul_f32 v[88:89], v[122:123], v[78:79]
	v_pk_mul_f32 v[70:71], v[168:169], v[14:15] op_sel_hi:[0,1]
	v_pk_fma_f32 v[68:69], v[4:5], v[80:81], v[68:69]
	v_pk_fma_f32 v[88:89], v[124:125], v[80:81], v[88:89]
	v_pk_mul_f32 v[72:73], v[168:169], v[16:17] op_sel_hi:[0,1]
	v_add_f32_e32 v68, v68, v69
	v_add_f32_e32 v88, v88, v89
	v_pk_fma_f32 v[74:75], v[6:7], v[78:79], v[70:71]
	v_add_f32_dpp v68, v68, v68 quad_perm:[1,0,3,2] row_mask:0xf bank_mask:0xf bound_ctrl:1
	v_add_f32_dpp v88, v88, v88 row_ror:8 row_mask:0xf bank_mask:0xf bound_ctrl:1
	v_pk_fma_f32 v[76:77], v[8:9], v[80:81], v[72:73]
	v_add_f32_dpp v68, v68, v68 quad_perm:[2,3,0,1] row_mask:0xf bank_mask:0xf bound_ctrl:1
	ds_write2st64_b32 v86, v82, v88 offset0:44 offset1:46
	ds_read_b128 v[46:49], v84 offset:6656
	v_add_f32_dpp v68, v68, v68 row_half_mirror row_mask:0xf bank_mask:0xf bound_ctrl:1
	ds_read_b128 v[50:53], v84 offset:14848
	ds_read_b128 v[54:57], v84 offset:23040
	v_add_f32_dpp v68, v68, v68 row_ror:8 row_mask:0xf bank_mask:0xf bound_ctrl:1
	ds_read_b128 v[58:61], v84 offset:31232
	ds_read_b128 v[62:65], v84 offset:39424
	v_pk_fma_f32 v[78:79], v[10:11], v[68:69], v[74:75] op_sel_hi:[1,0,1] neg_lo:[0,1,0] neg_hi:[0,1,0]
	v_pk_fma_f32 v[80:81], v[12:13], v[68:69], v[76:77] op_sel_hi:[1,0,1] neg_lo:[0,1,0] neg_hi:[0,1,0]
	s_waitcnt lgkmcnt(6)
	v_pk_mul_f32 v[68:69], v[24:25], v[78:79]
	v_pk_mul_f32 v[82:83], v[18:19], v[78:79]
	v_pk_mul_f32 v[70:71], v[168:169], v[36:37] op_sel:[1,0]
	v_pk_fma_f32 v[68:69], v[26:27], v[80:81], v[68:69]
	v_pk_fma_f32 v[82:83], v[20:21], v[80:81], v[82:83]
	v_pk_mul_f32 v[72:73], v[168:169], v[38:39] op_sel:[1,0]
	v_add_f32_e32 v68, v68, v69
	v_add_f32_e32 v82, v82, v83
	v_pk_fma_f32 v[74:75], v[28:29], v[78:79], v[70:71]
	v_add_f32_dpp v68, v68, v68 quad_perm:[1,0,3,2] row_mask:0xf bank_mask:0xf bound_ctrl:1
	v_add_f32_dpp v82, v82, v82 row_ror:8 row_mask:0xf bank_mask:0xf bound_ctrl:1
	v_pk_fma_f32 v[76:77], v[30:31], v[80:81], v[72:73]
	v_add_f32_dpp v68, v68, v68 quad_perm:[2,3,0,1] row_mask:0xf bank_mask:0xf bound_ctrl:1
	ds_read_b128 v[106:109], v84 offset:6912
	ds_read_b128 v[110:113], v84 offset:15104
	v_add_f32_dpp v68, v68, v68 row_half_mirror row_mask:0xf bank_mask:0xf bound_ctrl:1
	ds_read_b128 v[114:117], v84 offset:23296
	ds_read_b128 v[118:121], v84 offset:31488
	v_add_f32_dpp v68, v68, v68 row_ror:8 row_mask:0xf bank_mask:0xf bound_ctrl:1
	ds_read_b128 v[122:125], v84 offset:39680
	v_pk_fma_f32 v[78:79], v[32:33], v[68:69], v[74:75] op_sel_hi:[1,0,1] neg_lo:[0,1,0] neg_hi:[0,1,0]
	v_pk_fma_f32 v[80:81], v[34:35], v[68:69], v[76:77] op_sel_hi:[1,0,1] neg_lo:[0,1,0] neg_hi:[0,1,0]
	s_waitcnt lgkmcnt(5)
	v_pk_mul_f32 v[68:69], v[46:47], v[78:79]
	v_pk_mul_f32 v[88:89], v[40:41], v[78:79]
	v_pk_mul_f32 v[70:71], v[170:171], v[58:59] op_sel_hi:[0,1]
	v_pk_fma_f32 v[68:69], v[48:49], v[80:81], v[68:69]
	v_pk_fma_f32 v[88:89], v[42:43], v[80:81], v[88:89]
	v_pk_mul_f32 v[72:73], v[170:171], v[60:61] op_sel_hi:[0,1]
	v_add_f32_e32 v68, v68, v69
	v_add_f32_e32 v88, v88, v89
	v_pk_fma_f32 v[74:75], v[50:51], v[78:79], v[70:71]
	v_add_f32_dpp v68, v68, v68 quad_perm:[1,0,3,2] row_mask:0xf bank_mask:0xf bound_ctrl:1
	v_add_f32_dpp v88, v88, v88 row_ror:8 row_mask:0xf bank_mask:0xf bound_ctrl:1
	v_pk_fma_f32 v[76:77], v[52:53], v[80:81], v[72:73]
	v_add_f32_dpp v68, v68, v68 quad_perm:[2,3,0,1] row_mask:0xf bank_mask:0xf bound_ctrl:1
	ds_write2st64_b32 v86, v82, v88 offset0:48 offset1:50
	ds_read_b128 v[2:5], v84 offset:7168
	v_add_f32_dpp v68, v68, v68 row_half_mirror row_mask:0xf bank_mask:0xf bound_ctrl:1
	ds_read_b128 v[6:9], v84 offset:15360
	ds_read_b128 v[10:13], v84 offset:23552
	v_add_f32_dpp v68, v68, v68 row_ror:8 row_mask:0xf bank_mask:0xf bound_ctrl:1
	ds_read_b128 v[14:17], v84 offset:31744
	ds_read_b128 v[18:21], v84 offset:39936
	v_pk_fma_f32 v[78:79], v[54:55], v[68:69], v[74:75] op_sel_hi:[1,0,1] neg_lo:[0,1,0] neg_hi:[0,1,0]
	v_pk_fma_f32 v[80:81], v[56:57], v[68:69], v[76:77] op_sel_hi:[1,0,1] neg_lo:[0,1,0] neg_hi:[0,1,0]
	s_waitcnt lgkmcnt(6)
	v_pk_mul_f32 v[68:69], v[106:107], v[78:79]
	v_pk_mul_f32 v[82:83], v[62:63], v[78:79]
	v_pk_mul_f32 v[70:71], v[170:171], v[118:119] op_sel:[1,0]
	v_pk_fma_f32 v[68:69], v[108:109], v[80:81], v[68:69]
	v_pk_fma_f32 v[82:83], v[64:65], v[80:81], v[82:83]
	v_pk_mul_f32 v[72:73], v[170:171], v[120:121] op_sel:[1,0]
	v_add_f32_e32 v68, v68, v69
	v_add_f32_e32 v82, v82, v83
	v_pk_fma_f32 v[74:75], v[110:111], v[78:79], v[70:71]
	v_add_f32_dpp v68, v68, v68 quad_perm:[1,0,3,2] row_mask:0xf bank_mask:0xf bound_ctrl:1
	v_add_f32_dpp v82, v82, v82 row_ror:8 row_mask:0xf bank_mask:0xf bound_ctrl:1
	v_pk_fma_f32 v[76:77], v[112:113], v[80:81], v[72:73]
	v_add_f32_dpp v68, v68, v68 quad_perm:[2,3,0,1] row_mask:0xf bank_mask:0xf bound_ctrl:1
	ds_read_b128 v[24:27], v84 offset:7424
	ds_read_b128 v[28:31], v84 offset:15616
	v_add_f32_dpp v68, v68, v68 row_half_mirror row_mask:0xf bank_mask:0xf bound_ctrl:1
	ds_read_b128 v[32:35], v84 offset:23808
	ds_read_b128 v[36:39], v84 offset:32000
	v_add_f32_dpp v68, v68, v68 row_ror:8 row_mask:0xf bank_mask:0xf bound_ctrl:1
	ds_read_b128 v[40:43], v84 offset:40192
	v_pk_fma_f32 v[78:79], v[114:115], v[68:69], v[74:75] op_sel_hi:[1,0,1] neg_lo:[0,1,0] neg_hi:[0,1,0]
	v_pk_fma_f32 v[80:81], v[116:117], v[68:69], v[76:77] op_sel_hi:[1,0,1] neg_lo:[0,1,0] neg_hi:[0,1,0]
	s_waitcnt lgkmcnt(5)
	v_pk_mul_f32 v[68:69], v[2:3], v[78:79]
	v_pk_mul_f32 v[88:89], v[122:123], v[78:79]
	v_pk_mul_f32 v[70:71], v[172:173], v[14:15] op_sel_hi:[0,1]
	v_pk_fma_f32 v[68:69], v[4:5], v[80:81], v[68:69]
	v_pk_fma_f32 v[88:89], v[124:125], v[80:81], v[88:89]
	v_pk_mul_f32 v[72:73], v[172:173], v[16:17] op_sel_hi:[0,1]
	v_add_f32_e32 v68, v68, v69
	v_add_f32_e32 v88, v88, v89
	v_pk_fma_f32 v[74:75], v[6:7], v[78:79], v[70:71]
	v_add_f32_dpp v68, v68, v68 quad_perm:[1,0,3,2] row_mask:0xf bank_mask:0xf bound_ctrl:1
	v_add_f32_dpp v88, v88, v88 row_ror:8 row_mask:0xf bank_mask:0xf bound_ctrl:1
	v_pk_fma_f32 v[76:77], v[8:9], v[80:81], v[72:73]
	v_add_f32_dpp v68, v68, v68 quad_perm:[2,3,0,1] row_mask:0xf bank_mask:0xf bound_ctrl:1
	ds_write2st64_b32 v86, v82, v88 offset0:52 offset1:54
	ds_read_b128 v[46:49], v84 offset:7680
	v_add_f32_dpp v68, v68, v68 row_half_mirror row_mask:0xf bank_mask:0xf bound_ctrl:1
	ds_read_b128 v[50:53], v84 offset:15872
	ds_read_b128 v[54:57], v84 offset:24064
	v_add_f32_dpp v68, v68, v68 row_ror:8 row_mask:0xf bank_mask:0xf bound_ctrl:1
	ds_read_b128 v[58:61], v84 offset:32256
	ds_read_b128 v[62:65], v84 offset:40448
	v_pk_fma_f32 v[78:79], v[10:11], v[68:69], v[74:75] op_sel_hi:[1,0,1] neg_lo:[0,1,0] neg_hi:[0,1,0]
	v_pk_fma_f32 v[80:81], v[12:13], v[68:69], v[76:77] op_sel_hi:[1,0,1] neg_lo:[0,1,0] neg_hi:[0,1,0]
	s_waitcnt lgkmcnt(6)
	v_pk_mul_f32 v[68:69], v[24:25], v[78:79]
	v_pk_mul_f32 v[82:83], v[18:19], v[78:79]
	v_pk_mul_f32 v[70:71], v[172:173], v[36:37] op_sel:[1,0]
	v_pk_fma_f32 v[68:69], v[26:27], v[80:81], v[68:69]
	v_pk_fma_f32 v[82:83], v[20:21], v[80:81], v[82:83]
	v_pk_mul_f32 v[72:73], v[172:173], v[38:39] op_sel:[1,0]
	v_add_f32_e32 v68, v68, v69
	v_add_f32_e32 v82, v82, v83
	v_pk_fma_f32 v[74:75], v[28:29], v[78:79], v[70:71]
	v_add_f32_dpp v68, v68, v68 quad_perm:[1,0,3,2] row_mask:0xf bank_mask:0xf bound_ctrl:1
	v_add_f32_dpp v82, v82, v82 row_ror:8 row_mask:0xf bank_mask:0xf bound_ctrl:1
	v_pk_fma_f32 v[76:77], v[30:31], v[80:81], v[72:73]
	v_add_f32_dpp v68, v68, v68 quad_perm:[2,3,0,1] row_mask:0xf bank_mask:0xf bound_ctrl:1
	ds_read_b128 v[106:109], v84 offset:7936
	ds_read_b128 v[110:113], v84 offset:16128
	v_add_f32_dpp v68, v68, v68 row_half_mirror row_mask:0xf bank_mask:0xf bound_ctrl:1
	ds_read_b128 v[114:117], v84 offset:24320
	ds_read_b128 v[118:121], v84 offset:32512
	v_add_f32_dpp v68, v68, v68 row_ror:8 row_mask:0xf bank_mask:0xf bound_ctrl:1
	ds_read_b128 v[122:125], v84 offset:40704
	v_pk_fma_f32 v[78:79], v[32:33], v[68:69], v[74:75] op_sel_hi:[1,0,1] neg_lo:[0,1,0] neg_hi:[0,1,0]
	v_pk_fma_f32 v[80:81], v[34:35], v[68:69], v[76:77] op_sel_hi:[1,0,1] neg_lo:[0,1,0] neg_hi:[0,1,0]
	s_waitcnt lgkmcnt(5)
	v_pk_mul_f32 v[68:69], v[46:47], v[78:79]
	v_pk_mul_f32 v[88:89], v[40:41], v[78:79]
	v_pk_mul_f32 v[70:71], v[174:175], v[58:59] op_sel_hi:[0,1]
	v_pk_fma_f32 v[68:69], v[48:49], v[80:81], v[68:69]
	v_pk_fma_f32 v[88:89], v[42:43], v[80:81], v[88:89]
	v_pk_mul_f32 v[72:73], v[174:175], v[60:61] op_sel_hi:[0,1]
	v_add_f32_e32 v68, v68, v69
	v_add_f32_e32 v88, v88, v89
	v_pk_fma_f32 v[74:75], v[50:51], v[78:79], v[70:71]
	v_add_f32_dpp v68, v68, v68 quad_perm:[1,0,3,2] row_mask:0xf bank_mask:0xf bound_ctrl:1
	v_add_f32_dpp v88, v88, v88 row_ror:8 row_mask:0xf bank_mask:0xf bound_ctrl:1
	v_pk_fma_f32 v[76:77], v[52:53], v[80:81], v[72:73]
	v_add_f32_dpp v68, v68, v68 quad_perm:[2,3,0,1] row_mask:0xf bank_mask:0xf bound_ctrl:1
	ds_write2st64_b32 v86, v82, v88 offset0:56 offset1:58
	s_nop 0
	v_add_f32_dpp v68, v68, v68 row_half_mirror row_mask:0xf bank_mask:0xf bound_ctrl:1
	s_nop 1
	v_add_f32_dpp v68, v68, v68 row_ror:8 row_mask:0xf bank_mask:0xf bound_ctrl:1
	v_pk_fma_f32 v[78:79], v[54:55], v[68:69], v[74:75] op_sel_hi:[1,0,1] neg_lo:[0,1,0] neg_hi:[0,1,0]
	v_pk_fma_f32 v[80:81], v[56:57], v[68:69], v[76:77] op_sel_hi:[1,0,1] neg_lo:[0,1,0] neg_hi:[0,1,0]
	s_waitcnt lgkmcnt(1)
	v_pk_mul_f32 v[68:69], v[106:107], v[78:79]
	v_pk_mul_f32 v[82:83], v[62:63], v[78:79]
	v_pk_mul_f32 v[70:71], v[174:175], v[118:119] op_sel:[1,0]
	v_pk_fma_f32 v[68:69], v[108:109], v[80:81], v[68:69]
	v_pk_fma_f32 v[82:83], v[64:65], v[80:81], v[82:83]
	v_pk_mul_f32 v[72:73], v[174:175], v[120:121] op_sel:[1,0]
	v_add_f32_e32 v68, v68, v69
	v_add_f32_e32 v82, v82, v83
	v_pk_fma_f32 v[74:75], v[110:111], v[78:79], v[70:71]
	v_add_f32_dpp v68, v68, v68 quad_perm:[1,0,3,2] row_mask:0xf bank_mask:0xf bound_ctrl:1
	v_add_f32_dpp v82, v82, v82 row_ror:8 row_mask:0xf bank_mask:0xf bound_ctrl:1
	v_pk_fma_f32 v[76:77], v[112:113], v[80:81], v[72:73]
	v_add_f32_dpp v68, v68, v68 quad_perm:[2,3,0,1] row_mask:0xf bank_mask:0xf bound_ctrl:1
	s_nop 1
	v_add_f32_dpp v68, v68, v68 row_half_mirror row_mask:0xf bank_mask:0xf bound_ctrl:1
	s_nop 1
	v_add_f32_dpp v68, v68, v68 row_ror:8 row_mask:0xf bank_mask:0xf bound_ctrl:1
	v_pk_fma_f32 v[78:79], v[114:115], v[68:69], v[74:75] op_sel_hi:[1,0,1] neg_lo:[0,1,0] neg_hi:[0,1,0]
	v_pk_fma_f32 v[80:81], v[116:117], v[68:69], v[76:77] op_sel_hi:[1,0,1] neg_lo:[0,1,0] neg_hi:[0,1,0]
	v_pk_mul_f32 v[88:89], v[122:123], v[78:79]
	v_pk_fma_f32 v[88:89], v[124:125], v[80:81], v[88:89]
	v_add_f32_e32 v88, v88, v89
	s_nop 1
	v_add_f32_dpp v88, v88, v88 row_ror:8 row_mask:0xf bank_mask:0xf bound_ctrl:1
	ds_write2st64_b32 v86, v82, v88 offset0:60 offset1:62
	v_add_u32_e32 v101, 1, v101
.LBB0_623:
	s_andn2_saveexec_b64 s[92:93], s[14:15]
	s_cbranch_execz .LBB0_618
	s_waitcnt vmcnt(0) lgkmcnt(0)
	s_movk_i32 s0, 0x107
	v_add_u32_e32 v64, 1, v101
	v_cmp_ne_u32_e64 s[14:15], s0, v101
	s_and_saveexec_b64 s[16:17], s[14:15]
	s_cbranch_execz .Lscan_stage_done
	v_pk_mul_f32 v[60:61], v[42:43], v[34:35]
	v_pk_mul_f32 v[58:59], v[44:45], v[36:37]
	v_pk_mul_f32 v[66:67], v[60:61], v[60:61]
	v_pk_mul_f32 v[62:63], v[58:59], v[58:59]
	v_add_f32_e32 v0, v66, v67
	v_add_f32_e32 v0, v62, v0
	v_add_f32_e32 v0, v63, v0
	v_and_b32_e32 v63, 1, v64
	v_lshlrev_b32_e32 v70, 16, v111
	v_add_f32_dpp v0, v0, v0 quad_perm:[1,0,3,2] row_mask:0xf bank_mask:0xf bound_ctrl:1
	v_and_b32_e32 v71, 0xffff0000, v111
	v_lshlrev_b32_e32 v74, 16, v112
	v_add_f32_dpp v0, v0, v0 quad_perm:[2,3,0,1] row_mask:0xf bank_mask:0xf bound_ctrl:1
	v_and_b32_e32 v75, 0xffff0000, v112
	v_lshlrev_b32_e32 v76, 16, v113
	v_add_f32_dpp v0, v0, v0 row_half_mirror row_mask:0xf bank_mask:0xf bound_ctrl:1
	v_and_b32_e32 v77, 0xffff0000, v113
	s_nop 0
	v_add_f32_dpp v0, v0, v0 row_ror:8 row_mask:0xf bank_mask:0xf bound_ctrl:1
	v_mul_f32_e32 v62, 0x4f800000, v0
	v_cmp_gt_f32_e32 vcc, s74, v0
	s_nop 1
	v_cndmask_b32_e32 v0, v0, v62, vcc
	v_sqrt_f32_e32 v62, v0
	s_nop 0
	v_add_u32_e32 v65, -1, v62
	v_fma_f32 v66, -v65, v62, v0
	v_cmp_ge_f32_e64 s[14:15], 0, v66
	v_add_u32_e32 v66, 1, v62
	s_nop 0
	v_cndmask_b32_e64 v65, v62, v65, s[14:15]
	v_fma_f32 v62, -v66, v62, v0
	v_cmp_lt_f32_e64 s[14:15], 0, v62
	s_nop 1
	v_cndmask_b32_e64 v62, v65, v66, s[14:15]
	v_mul_f32_e32 v65, 0x37800000, v62
	v_cndmask_b32_e32 v62, v62, v65, vcc
	v_cmp_class_f32_e32 vcc, v0, v163
	s_nop 1
	v_cndmask_b32_e32 v0, v62, v0, vcc
	v_max_f32_e32 v62, 0x2b8cbccc, v0
	v_div_scale_f32 v65, s[0:1], v62, v62, 1.0
	v_rcp_f32_e32 v66, v65
	v_cmp_eq_u32_e32 vcc, 1, v63
	v_fma_f32 v63, -v65, v66, 1.0
	s_nop 0
	v_cndmask_b32_e32 v0, 0, v167, vcc
	v_fmac_f32_e32 v66, v63, v66
	v_div_scale_f32 v63, vcc, 1.0, v62, 1.0
	v_mul_f32_e32 v67, v63, v66
	v_fma_f32 v68, -v65, v67, v63
	v_fmac_f32_e32 v67, v68, v66
	v_fma_f32 v63, -v65, v67, v63
	v_div_fmas_f32 v63, v63, v66, v67
	v_div_fixup_f32 v66, v63, v62, 1.0
	v_pk_mul_f32 v[62:63], v[58:59], v[66:67] op_sel_hi:[1,0]
	v_lshlrev_b32_e32 v58, 16, v110
	v_and_b32_e32 v59, 0xffff0000, v110
	v_pk_mul_f32 v[60:61], v[60:61], v[66:67] op_sel_hi:[1,0]
	v_pk_add_f32 v[66:67], v[70:71], -1.0 op_sel_hi:[1,0]
	v_pk_add_f32 v[68:69], v[58:59], -1.0 op_sel_hi:[1,0]
	v_pk_fma_f32 v[66:67], v[48:49], v[66:67], 1.0 op_sel_hi:[1,1,0]
	v_pk_fma_f32 v[72:73], v[46:47], v[68:69], 1.0 op_sel_hi:[1,1,0]
	v_add_u32_e32 v0, 0, v0
	v_pk_mul_f32 v[68:69], v[36:37], v[66:67]
	v_pk_mul_f32 v[66:67], v[34:35], v[72:73]
	v_pk_mul_f32 v[72:73], v[62:63], v[70:71]
	v_pk_mul_f32 v[70:71], v[60:61], v[58:59]
	v_lshlrev_b32_e32 v58, 2, v98
	v_add3_u32 v59, v0, v165, v58
	ds_write_b128 v59, v[60:63]
	ds_write_b128 v59, v[38:41] offset:8192
	ds_write_b128 v59, v[70:73] offset:16384
	ds_write_b128 v59, v[66:69] offset:24576
	ds_write_b128 v59, v[74:77] offset:32768
	s_and_saveexec_b64 s[0:1], s[10:11]
	s_cbranch_execz .LBB0_728
	v_lshlrev_b32_e32 v60, 16, v106
	v_and_b32_e32 v61, 0xffff0000, v106
	v_lshlrev_b32_e32 v62, 16, v107
	v_and_b32_e32 v63, 0xffff0000, v107
	v_lshrrev_b32_e32 v184, 4, v142
	v_lshl_add_u32 v184, v98, 7, v184
	v_add_u32_e32 v184, 0xa000, v184
	v_add_u32_e32 v184, v184, v0
	ds_write2_b32 v184, v60, v61 offset1:32
	ds_write2_b32 v184, v62, v63 offset0:64 offset1:96
.LBB0_728:
	s_or_b64 exec, exec, s[0:1]
	v_pk_mul_f32 v[66:67], v[42:43], v[50:51]
	v_pk_mul_f32 v[60:61], v[44:45], v[52:53]
	v_pk_mul_f32 v[68:69], v[66:67], v[66:67]
	v_pk_mul_f32 v[62:63], v[60:61], v[60:61]
	v_add_f32_e32 v59, v68, v69
	v_add_f32_e32 v59, v62, v59
	v_add_f32_e32 v59, v63, v59
	v_lshlrev_b32_e32 v70, 16, v114
	v_and_b32_e32 v71, 0xffff0000, v114
	v_add_f32_dpp v59, v59, v59 quad_perm:[1,0,3,2] row_mask:0xf bank_mask:0xf bound_ctrl:1
	v_lshlrev_b32_e32 v72, 16, v115
	v_and_b32_e32 v73, 0xffff0000, v115
	v_add_f32_dpp v59, v59, v59 quad_perm:[2,3,0,1] row_mask:0xf bank_mask:0xf bound_ctrl:1
	v_lshlrev_b32_e32 v76, 16, v117
	v_and_b32_e32 v77, 0xffff0000, v117
	v_add_f32_dpp v59, v59, v59 row_half_mirror row_mask:0xf bank_mask:0xf bound_ctrl:1
	s_nop 1
	v_add_f32_dpp v59, v59, v59 row_ror:8 row_mask:0xf bank_mask:0xf bound_ctrl:1
	v_mul_f32_e32 v62, 0x4f800000, v59
	v_cmp_gt_f32_e32 vcc, s74, v59
	s_nop 1
	v_cndmask_b32_e32 v59, v59, v62, vcc
	v_sqrt_f32_e32 v62, v59
	s_nop 0
	v_add_u32_e32 v63, -1, v62
	v_fma_f32 v65, -v63, v62, v59
	v_cmp_ge_f32_e64 s[14:15], 0, v65
	v_add_u32_e32 v65, 1, v62
	s_nop 0
	v_cndmask_b32_e64 v63, v62, v63, s[14:15]
	v_fma_f32 v62, -v65, v62, v59
	v_cmp_lt_f32_e64 s[14:15], 0, v62
	s_nop 1
	v_cndmask_b32_e64 v62, v63, v65, s[14:15]
	v_mul_f32_e32 v63, 0x37800000, v62
	v_cndmask_b32_e32 v62, v62, v63, vcc
	v_cmp_class_f32_e32 vcc, v59, v163
	s_nop 1
	v_cndmask_b32_e32 v59, v62, v59, vcc
	v_max_f32_e32 v59, 0x2b8cbccc, v59
	v_div_scale_f32 v62, s[0:1], v59, v59, 1.0
	v_rcp_f32_e32 v63, v62
	s_nop 0
	v_fma_f32 v65, -v62, v63, 1.0
	v_fmac_f32_e32 v63, v65, v63
	v_div_scale_f32 v65, vcc, 1.0, v59, 1.0
	v_mul_f32_e32 v68, v65, v63
	v_fma_f32 v69, -v62, v68, v65
	v_fmac_f32_e32 v68, v69, v63
	v_fma_f32 v62, -v62, v68, v65
	v_div_fmas_f32 v62, v62, v63, v68
	v_div_fixup_f32 v68, v62, v59, 1.0
	v_pk_mul_f32 v[62:63], v[60:61], v[68:69] op_sel_hi:[1,0]
	v_pk_mul_f32 v[60:61], v[66:67], v[68:69] op_sel_hi:[1,0]
	v_pk_add_f32 v[66:67], v[72:73], -1.0 op_sel_hi:[1,0]
	v_pk_add_f32 v[68:69], v[70:71], -1.0 op_sel_hi:[1,0]
	v_lshlrev_b32_e32 v59, 2, v144
	v_pk_fma_f32 v[74:75], v[46:47], v[68:69], 1.0 op_sel_hi:[1,1,0]
	v_pk_fma_f32 v[66:67], v[48:49], v[66:67], 1.0 op_sel_hi:[1,1,0]
	v_add3_u32 v59, v0, v59, v58
	v_pk_mul_f32 v[68:69], v[52:53], v[66:67]
	v_pk_mul_f32 v[66:67], v[50:51], v[74:75]
	v_pk_mul_f32 v[72:73], v[62:63], v[72:73]
	v_pk_mul_f32 v[70:71], v[60:61], v[70:71]
	v_lshlrev_b32_e32 v74, 16, v116
	v_and_b32_e32 v75, 0xffff0000, v116
	ds_write_b128 v59, v[60:63]
	ds_write_b128 v59, v[54:57] offset:8192
	ds_write_b128 v59, v[70:73] offset:16384
	ds_write_b128 v59, v[66:69] offset:24576
	ds_write_b128 v59, v[74:77] offset:32768
	s_and_saveexec_b64 s[0:1], s[10:11]
	s_cbranch_execz .Lscan_stage_tail
	v_lshlrev_b32_e32 v60, 16, v108
	v_and_b32_e32 v61, 0xffff0000, v108
	v_lshlrev_b32_e32 v62, 16, v109
	v_and_b32_e32 v63, 0xffff0000, v109
	v_lshrrev_b32_e32 v184, 4, v144
	v_lshl_add_u32 v184, v98, 7, v184
	v_add_u32_e32 v184, 0xa000, v184
	v_add_u32_e32 v184, v184, v0
	ds_write2_b32 v184, v60, v61 offset1:32
	ds_write2_b32 v184, v62, v63 offset0:64 offset1:96
